# P4 pass epilogue: packed f32 mul/add as scalar pairs
# speedup vs baseline: 1.0232x; 1.0038x over previous
.Lqh_skip:
	s_andn2_b64 vcc, exec, s[36:37]
	s_cbranch_vccz .LBB0_684
	v_mul_f32_e32 v20, v178, v20
	v_mul_f32_e32 v21, v178, v21
	v_mul_f32_e32 v50, v178, v50
	v_mul_f32_e32 v51, v178, v51
	v_mul_f32_e32 v48, v178, v48
	v_mul_f32_e32 v49, v178, v49
	v_mul_f32_e32 v46, v178, v46
	v_mul_f32_e32 v47, v178, v47
	v_mul_f32_e32 v44, v178, v44
	v_mul_f32_e32 v45, v178, v45
	v_mul_f32_e32 v42, v178, v42
	v_mul_f32_e32 v43, v178, v43
	v_mul_f32_e32 v40, v178, v40
	v_mul_f32_e32 v41, v178, v41
	v_mul_f32_e32 v38, v178, v38
	v_mul_f32_e32 v39, v178, v39
	v_mul_f32_e32 v36, v178, v36
	v_mul_f32_e32 v37, v178, v37
	v_mul_f32_e32 v34, v178, v34
	v_mul_f32_e32 v35, v178, v35
	v_mul_f32_e32 v32, v178, v32
	v_mul_f32_e32 v33, v178, v33
	v_mul_f32_e32 v30, v178, v30
	v_mul_f32_e32 v31, v178, v31
	v_mul_f32_e32 v28, v178, v28
	v_mul_f32_e32 v29, v178, v29
	v_mul_f32_e32 v26, v178, v26
	v_mul_f32_e32 v27, v178, v27
	v_mul_f32_e32 v24, v178, v24
	v_mul_f32_e32 v25, v178, v25
	v_mul_f32_e32 v22, v178, v22
	v_mul_f32_e32 v23, v178, v23
	v_mul_f32_e32 v68, v179, v68
	v_mul_f32_e32 v69, v179, v69
	v_mul_f32_e32 v82, v179, v82
	v_mul_f32_e32 v83, v179, v83
	v_mul_f32_e32 v80, v179, v80
	v_mul_f32_e32 v81, v179, v81
	v_mul_f32_e32 v78, v179, v78
	v_mul_f32_e32 v79, v179, v79
	v_mul_f32_e32 v76, v179, v76
	v_mul_f32_e32 v77, v179, v77
	v_mul_f32_e32 v74, v179, v74
	v_mul_f32_e32 v75, v179, v75
	v_mul_f32_e32 v72, v179, v72
	v_mul_f32_e32 v73, v179, v73
	v_mul_f32_e32 v70, v179, v70
	v_mul_f32_e32 v71, v179, v71
	v_mul_f32_e32 v52, v179, v52
	v_mul_f32_e32 v53, v179, v53
	v_mul_f32_e32 v66, v179, v66
	v_mul_f32_e32 v67, v179, v67
	v_mul_f32_e32 v64, v179, v64
	v_mul_f32_e32 v65, v179, v65
	v_mul_f32_e32 v62, v179, v62
	v_mul_f32_e32 v63, v179, v63
	v_mul_f32_e32 v60, v179, v60
	v_mul_f32_e32 v61, v179, v61
	v_mul_f32_e32 v58, v179, v58
	v_mul_f32_e32 v59, v179, v59
	v_mul_f32_e32 v56, v179, v56
	v_mul_f32_e32 v57, v179, v57
	v_mul_f32_e32 v54, v179, v54
	v_mul_f32_e32 v55, v179, v55
	v_mul_f32_e32 v180, v178, v180
	v_mul_f32_e32 v181, v179, v181
.LBB0_684:
	s_nop 0
	v_mov_b32_e32 v4, v180
	v_mov_b32_e32 v5, v181
	s_andn2_b64 vcc, exec, s[26:27]
	v_permlane32_swap_b32_e32 v180, v4
	v_permlane32_swap_b32_e32 v181, v5
	v_add_f32_e32 v4, v180, v4
	v_add_f32_e32 v5, v181, v5
	s_cbranch_vccnz .LBB0_686
	s_add_i32 s0, s65, s53
	s_ashr_i32 s1, s0, 31
	s_lshl_b64 s[0:1], s[0:1], 2
	s_add_u32 s0, s82, s0
	s_addc_u32 s1, s83, s1
	global_load_dwordx2 v[6:7], v2, s[0:1]
	s_lshl_b32 s0, s65, 2
	s_add_i32 s0, s0, 0
	s_add_i32 s0, s0, 0x24200
	v_mov_b32_e32 v3, s0
	ds_read_b64 v[8:9], v3
	s_waitcnt vmcnt(0) lgkmcnt(0)
	v_sub_f32_e32 v3, v6, v8
	v_sub_f32_e32 v6, v7, v9
	v_mul_f32_e32 v3, 0x3fb8aa3b, v3
	v_mul_f32_e32 v7, 0x3fb8aa3b, v6
	v_exp_f32_e32 v6, v3
	v_exp_f32_e32 v7, v7
	s_nop 0
	v_add_f32_e32 v4, v4, v6
	v_add_f32_e32 v5, v5, v7

.Lgw1:
	v_mul_f32_e32 v4, v210, v3
	v_fma_f32 v3, -v6, v7, 1.0
	v_fmac_f32_e32 v7, v3, v7
	v_div_scale_f32 v3, vcc, 1.0, v5, 1.0
	v_mul_f32_e32 v8, v3, v7
	v_fma_f32 v9, -v6, v8, v3
	v_fmac_f32_e32 v8, v9, v7
	v_fma_f32 v3, -v6, v8, v3
	v_div_fmas_f32 v3, v3, v7, v8
	v_div_fixup_f32 v3, v3, v5, 1.0
	v_cmp_lt_f32_e32 vcc, 0, v5
	v_mul_f32_e32 v88, v20, v4
	v_mul_f32_e32 v89, v21, v4
	v_mul_f32_e32 v84, v36, v4
	v_mul_f32_e32 v85, v37, v4
	v_cndmask_b32_e32 v3, 0, v3, vcc
	v_mul_f32_e32 v6, v211, v3
	v_mul_f32_e32 v90, v68, v6
	v_mul_f32_e32 v91, v69, v6
	v_mul_f32_e32 v68, v52, v6
	v_mul_f32_e32 v69, v53, v6
	v_mul_f32_e32 v92, v22, v4
	v_mul_f32_e32 v93, v23, v4
	v_mul_f32_e32 v86, v38, v4
	v_mul_f32_e32 v87, v39, v4
	v_mul_f32_e32 v96, v70, v6
	v_mul_f32_e32 v97, v71, v6
	v_mul_f32_e32 v54, v54, v6
	v_mul_f32_e32 v55, v55, v6
	v_mul_f32_e32 v98, v24, v4
	v_mul_f32_e32 v99, v25, v4
	v_mul_f32_e32 v70, v40, v4
	v_mul_f32_e32 v71, v41, v4
	v_mul_f32_e32 v100, v72, v6
	v_mul_f32_e32 v101, v73, v6
	v_mul_f32_e32 v56, v56, v6
	v_mul_f32_e32 v57, v57, v6
	v_mul_f32_e32 v102, v26, v4
	v_mul_f32_e32 v103, v27, v4
	v_mul_f32_e32 v72, v42, v4
	v_mul_f32_e32 v73, v43, v4
	v_mul_f32_e32 v104, v74, v6
	v_mul_f32_e32 v105, v75, v6
	v_mul_f32_e32 v58, v58, v6
	v_mul_f32_e32 v59, v59, v6
	v_mul_f32_e32 v94, v28, v4
	v_mul_f32_e32 v95, v29, v4
	v_mul_f32_e32 v52, v44, v4
	v_mul_f32_e32 v53, v45, v4
	v_mul_f32_e32 v74, v76, v6
	v_mul_f32_e32 v75, v77, v6
	v_mul_f32_e32 v16, v60, v6
	v_mul_f32_e32 v17, v61, v6
	v_mul_f32_e32 v76, v30, v4
	v_mul_f32_e32 v77, v31, v4
	v_mul_f32_e32 v46, v46, v4
	v_mul_f32_e32 v47, v47, v4
	v_mul_f32_e32 v60, v78, v6
	v_mul_f32_e32 v61, v79, v6
	v_mul_f32_e32 v40, v62, v6
	v_mul_f32_e32 v41, v63, v6
	v_mul_f32_e32 v78, v32, v4
	v_mul_f32_e32 v79, v33, v4
	v_mul_f32_e32 v48, v48, v4
	v_mul_f32_e32 v49, v49, v4
	v_mul_f32_e32 v62, v80, v6
	v_mul_f32_e32 v63, v81, v6
	v_mul_f32_e32 v42, v64, v6
	v_mul_f32_e32 v43, v65, v6
	v_mul_f32_e32 v80, v34, v4
	v_mul_f32_e32 v81, v35, v4
	v_mul_f32_e32 v50, v50, v4
	v_mul_f32_e32 v51, v51, v4
	v_mul_f32_e32 v64, v82, v6
	v_mul_f32_e32 v65, v83, v6
	s_andn2_b64 vcc, exec, s[24:25]
	v_mul_f32_e32 v44, v66, v6
	v_mul_f32_e32 v45, v67, v6
	s_cbranch_vccnz .LBB0_688
	ds_read_b128 v[12:15], v193
	ds_read_b128 v[20:23], v193 offset:2048
	ds_read_b128 v[8:11], v193 offset:4096
	ds_read_b128 v[4:7], v193 offset:6144
	ds_read_b128 v[24:27], v193 offset:1024
	s_waitcnt lgkmcnt(0)
	v_lshlrev_b32_e32 v28, 16, v12
	v_and_b32_e32 v29, 0xffff0000, v12
	v_add_f32_e32 v88, v88, v28
	v_add_f32_e32 v89, v89, v29
	v_lshlrev_b32_e32 v28, 16, v20
	v_and_b32_e32 v29, 0xffff0000, v20
	v_lshlrev_b32_e32 v12, 16, v13
	v_and_b32_e32 v13, 0xffff0000, v13
	v_add_f32_e32 v84, v84, v28
	v_add_f32_e32 v85, v85, v29
	v_lshlrev_b32_e32 v28, 16, v8
	v_and_b32_e32 v29, 0xffff0000, v8
	v_add_f32_e32 v92, v92, v12
	v_add_f32_e32 v93, v93, v13
	v_lshlrev_b32_e32 v12, 16, v14
	v_and_b32_e32 v13, 0xffff0000, v14
	v_add_f32_e32 v90, v90, v28
	v_add_f32_e32 v91, v91, v29
	v_lshlrev_b32_e32 v28, 16, v4
	v_and_b32_e32 v29, 0xffff0000, v4
	v_lshlrev_b32_e32 v4, 16, v5
	v_and_b32_e32 v5, 0xffff0000, v5
	v_add_f32_e32 v98, v98, v12
	v_add_f32_e32 v99, v99, v13
	v_lshlrev_b32_e32 v12, 16, v15
	v_and_b32_e32 v13, 0xffff0000, v15
	v_add_f32_e32 v54, v54, v4
	v_add_f32_e32 v55, v55, v5
	v_lshlrev_b32_e32 v4, 16, v6
	v_and_b32_e32 v5, 0xffff0000, v6
	v_add_f32_e32 v102, v102, v12
	v_add_f32_e32 v103, v103, v13
	ds_read_b128 v[12:15], v193 offset:3072
	v_lshlrev_b32_e32 v20, 16, v21
	v_and_b32_e32 v21, 0xffff0000, v21
	v_add_f32_e32 v56, v56, v4
	v_add_f32_e32 v57, v57, v5
	v_lshlrev_b32_e32 v4, 16, v7
	v_and_b32_e32 v5, 0xffff0000, v7
	v_add_f32_e32 v86, v86, v20
	v_add_f32_e32 v87, v87, v21
	v_lshlrev_b32_e32 v20, 16, v22
	v_and_b32_e32 v21, 0xffff0000, v22
	v_add_f32_e32 v58, v58, v4
	v_add_f32_e32 v59, v59, v5
	v_lshlrev_b32_e32 v4, 16, v24
	v_and_b32_e32 v5, 0xffff0000, v24
	v_add_f32_e32 v70, v70, v20
	v_add_f32_e32 v71, v71, v21
	v_lshlrev_b32_e32 v20, 16, v23
	v_and_b32_e32 v21, 0xffff0000, v23
	v_add_f32_e32 v94, v94, v4
	v_add_f32_e32 v95, v95, v5
	v_lshlrev_b32_e32 v4, 16, v25
	v_and_b32_e32 v5, 0xffff0000, v25
	v_add_f32_e32 v72, v72, v20
	v_add_f32_e32 v73, v73, v21
	ds_read_b128 v[20:23], v193 offset:5120
	v_add_f32_e32 v76, v76, v4
	v_add_f32_e32 v77, v77, v5
	v_lshlrev_b32_e32 v4, 16, v26
	v_and_b32_e32 v5, 0xffff0000, v26
	v_lshlrev_b32_e32 v8, 16, v9
	v_and_b32_e32 v9, 0xffff0000, v9
	v_add_f32_e32 v78, v78, v4
	v_add_f32_e32 v79, v79, v5
	v_lshlrev_b32_e32 v4, 16, v27
	v_and_b32_e32 v5, 0xffff0000, v27
	v_add_f32_e32 v96, v96, v8
	v_add_f32_e32 v97, v97, v9
	v_lshlrev_b32_e32 v8, 16, v10
	v_and_b32_e32 v9, 0xffff0000, v10
	v_add_f32_e32 v80, v80, v4
	v_add_f32_e32 v81, v81, v5
	s_waitcnt lgkmcnt(1)
	v_lshlrev_b32_e32 v4, 16, v12
	v_and_b32_e32 v5, 0xffff0000, v12
	v_add_f32_e32 v100, v100, v8
	v_add_f32_e32 v101, v101, v9
	v_lshlrev_b32_e32 v8, 16, v11
	v_and_b32_e32 v9, 0xffff0000, v11
	v_add_f32_e32 v52, v52, v4
	v_add_f32_e32 v53, v53, v5
	v_lshlrev_b32_e32 v4, 16, v13
	v_and_b32_e32 v5, 0xffff0000, v13
	v_add_f32_e32 v104, v104, v8
	v_add_f32_e32 v105, v105, v9
	ds_read_b128 v[8:11], v193 offset:7168
	v_add_f32_e32 v46, v46, v4
	v_add_f32_e32 v47, v47, v5
	v_lshlrev_b32_e32 v4, 16, v14
	v_and_b32_e32 v5, 0xffff0000, v14
	v_add_f32_e32 v48, v48, v4
	v_add_f32_e32 v49, v49, v5
	s_waitcnt lgkmcnt(1)
	v_lshlrev_b32_e32 v4, 16, v20
	v_and_b32_e32 v5, 0xffff0000, v20
	v_add_f32_e32 v74, v74, v4
	v_add_f32_e32 v75, v75, v5
	v_lshlrev_b32_e32 v4, 16, v21
	v_and_b32_e32 v5, 0xffff0000, v21
	v_add_f32_e32 v60, v60, v4
	v_add_f32_e32 v61, v61, v5
	v_lshlrev_b32_e32 v4, 16, v22
	v_and_b32_e32 v5, 0xffff0000, v22
	v_add_f32_e32 v62, v62, v4
	v_add_f32_e32 v63, v63, v5
	v_lshlrev_b32_e32 v4, 16, v23
	v_and_b32_e32 v5, 0xffff0000, v23
	v_add_f32_e32 v64, v64, v4
	v_add_f32_e32 v65, v65, v5
	s_waitcnt lgkmcnt(0)
	v_lshlrev_b32_e32 v4, 16, v8
	v_and_b32_e32 v5, 0xffff0000, v8
	v_add_f32_e32 v16, v16, v4
	v_add_f32_e32 v17, v17, v5
	v_lshlrev_b32_e32 v4, 16, v9
	v_and_b32_e32 v5, 0xffff0000, v9
	v_lshlrev_b32_e32 v3, 16, v15
	v_add_f32_e32 v40, v40, v4
	v_add_f32_e32 v41, v41, v5
	v_lshlrev_b32_e32 v4, 16, v10
	v_and_b32_e32 v5, 0xffff0000, v10
	v_add_f32_e32 v50, v50, v3
	v_and_b32_e32 v3, 0xffff0000, v15
	v_add_f32_e32 v42, v42, v4
	v_add_f32_e32 v43, v43, v5
	v_lshlrev_b32_e32 v4, 16, v11
	v_and_b32_e32 v5, 0xffff0000, v11
	v_add_f32_e32 v68, v68, v28
	v_add_f32_e32 v69, v69, v29
	v_add_f32_e32 v51, v51, v3
	v_add_f32_e32 v44, v44, v4
	v_add_f32_e32 v45, v45, v5

.LBB0_691:
	s_add_i32 s65, s65, s53
	s_add_i32 s66, s66, s53
	s_lshl_b32 s0, s65, 6
	s_lshl_b32 s1, s66, 6
	s_add_i32 s24, s0, s47
	s_add_i32 s0, s1, s47
	s_ashr_i32 s25, s24, 31
	s_ashr_i32 s1, s0, 31
	v_lshl_add_u64 v[82:83], s[24:25], 1, v[176:177]
	v_lshl_add_u64 v[66:67], s[0:1], 1, v[176:177]
	s_waitcnt vmcnt(0)
	v_mov_b64_e32 v[28:29], v[214:215]
	v_mov_b64_e32 v[30:31], v[216:217]
	v_mov_b64_e32 v[24:25], v[218:219]
	v_mov_b64_e32 v[26:27], v[220:221]
	v_mov_b64_e32 v[4:5], v[222:223]
	v_mov_b64_e32 v[6:7], v[224:225]
	v_mov_b64_e32 v[36:37], v[226:227]
	v_mov_b64_e32 v[38:39], v[228:229]
	v_mov_b64_e32 v[32:33], v[230:231]
	v_mov_b64_e32 v[34:35], v[232:233]
	v_mov_b64_e32 v[12:13], v[244:245]
	v_mov_b64_e32 v[14:15], v[246:247]
	v_mov_b64_e32 v[20:21], v[248:249]
	v_mov_b64_e32 v[22:23], v[250:251]
	v_mov_b64_e32 v[8:9], v[252:253]
	v_mov_b64_e32 v[10:11], v[254:255]
	v_mov_b32_e32 v3, v30
	v_mov_b32_e32 v109, v26
	v_mov_b32_e32 v111, v27
	v_permlane32_swap_b32_e32 v28, v3
	v_permlane32_swap_b32_e32 v29, v31
	v_mov_b32_e32 v114, v6
	v_mov_b32_e32 v115, v7
	v_permlane32_swap_b32_e32 v24, v109
	v_permlane32_swap_b32_e32 v25, v111
	v_lshlrev_b32_e32 v6, 16, v28
	v_and_b32_e32 v7, 0xffff0000, v28
	v_lshlrev_b32_e32 v26, 16, v29
	v_and_b32_e32 v27, 0xffff0000, v29
	v_lshlrev_b32_e32 v28, 16, v3
	v_and_b32_e32 v29, 0xffff0000, v3
	v_lshlrev_b32_e32 v30, 16, v31
	v_and_b32_e32 v31, 0xffff0000, v31
	v_permlane32_swap_b32_e32 v5, v115
	v_lshlrev_b32_e32 v106, 16, v24
	v_and_b32_e32 v107, 0xffff0000, v24
	v_lshlrev_b32_e32 v24, 16, v25
	v_and_b32_e32 v25, 0xffff0000, v25
	v_lshlrev_b32_e32 v108, 16, v109
	v_and_b32_e32 v109, 0xffff0000, v109
	v_lshlrev_b32_e32 v110, 16, v111
	v_and_b32_e32 v111, 0xffff0000, v111
	v_mul_f32_e32 v6, v88, v6
	v_mul_f32_e32 v7, v89, v7
	v_mul_f32_e32 v26, v92, v26
	v_mul_f32_e32 v27, v93, v27
	v_mul_f32_e32 v28, v98, v28
	v_mul_f32_e32 v29, v99, v29
	v_mul_f32_e32 v30, v102, v30
	v_mul_f32_e32 v31, v103, v31
	v_mul_f32_e32 v88, v90, v106
	v_mul_f32_e32 v89, v91, v107
	v_mul_f32_e32 v90, v96, v24
	v_mul_f32_e32 v91, v97, v25
	v_mul_f32_e32 v92, v100, v108
	v_mul_f32_e32 v93, v101, v109
	v_mul_f32_e32 v96, v104, v110
	v_mul_f32_e32 v97, v105, v111
	v_cvt_pk_bf16_f32 v24, v6, v7
	v_cvt_pk_bf16_f32 v25, v26, v27
	v_cvt_pk_bf16_f32 v26, v28, v29
	v_cvt_pk_bf16_f32 v27, v30, v31
	v_lshlrev_b32_e32 v6, 16, v5
	v_and_b32_e32 v7, 0xffff0000, v5
	v_permlane32_swap_b32_e32 v4, v114
	v_cvt_pk_bf16_f32 v28, v88, v89
	v_cvt_pk_bf16_f32 v29, v90, v91
	v_cvt_pk_bf16_f32 v30, v92, v93
	v_cvt_pk_bf16_f32 v31, v96, v97
	v_permlane32_swap_b32_e32 v24, v26
	v_permlane32_swap_b32_e32 v25, v27
	v_mul_f32_e32 v6, v76, v6
	v_mul_f32_e32 v7, v77, v7
	v_lshlrev_b32_e32 v112, 16, v4
	v_and_b32_e32 v113, 0xffff0000, v4
	v_permlane32_swap_b32_e32 v28, v30
	v_permlane32_swap_b32_e32 v29, v31
	global_store_dwordx4 v[82:83], v[24:27], off
	global_store_dwordx4 v[66:67], v[28:31], off
	v_cvt_pk_bf16_f32 v5, v6, v7
	v_lshlrev_b32_e32 v6, 16, v114
	v_and_b32_e32 v7, 0xffff0000, v114
	v_lshlrev_b32_e32 v24, 16, v115
	v_and_b32_e32 v25, 0xffff0000, v115
	v_mul_f32_e32 v94, v94, v112
	v_mul_f32_e32 v95, v95, v113
	v_mul_f32_e32 v6, v78, v6
	v_mul_f32_e32 v7, v79, v7
	v_mul_f32_e32 v24, v80, v24
	v_mul_f32_e32 v25, v81, v25
	v_cvt_pk_bf16_f32 v4, v94, v95
	v_cvt_pk_bf16_f32 v6, v6, v7
	v_cvt_pk_bf16_f32 v7, v24, v25
	v_mov_b32_e32 v3, v38
	v_mov_b32_e32 v25, v39
	v_permlane32_swap_b32_e32 v4, v6
	v_permlane32_swap_b32_e32 v5, v7
	v_permlane32_swap_b32_e32 v36, v3
	v_permlane32_swap_b32_e32 v37, v25
	global_store_dwordx4 v[82:83], v[4:7], off offset:32
	v_lshlrev_b32_e32 v24, 16, v25
	v_and_b32_e32 v25, 0xffff0000, v25
	v_lshlrev_b32_e32 v4, 16, v36
	v_and_b32_e32 v5, 0xffff0000, v36
	v_lshlrev_b32_e32 v6, 16, v37
	v_and_b32_e32 v7, 0xffff0000, v37
	v_mul_f32_e32 v4, v74, v4
	v_mul_f32_e32 v5, v75, v5
	v_mul_f32_e32 v6, v60, v6
	v_mul_f32_e32 v7, v61, v7
	v_cvt_pk_bf16_f32 v4, v4, v5
	v_cvt_pk_bf16_f32 v5, v6, v7
	v_lshlrev_b32_e32 v6, 16, v3
	v_and_b32_e32 v7, 0xffff0000, v3
	v_mul_f32_e32 v6, v62, v6
	v_mul_f32_e32 v7, v63, v7
	v_mul_f32_e32 v24, v64, v24
	v_mul_f32_e32 v25, v65, v25
	v_cvt_pk_bf16_f32 v6, v6, v7
	v_cvt_pk_bf16_f32 v7, v24, v25
	v_mov_b32_e32 v3, v34
	v_mov_b32_e32 v25, v35
	v_permlane32_swap_b32_e32 v4, v6
	v_permlane32_swap_b32_e32 v5, v7
	v_permlane32_swap_b32_e32 v32, v3
	v_permlane32_swap_b32_e32 v33, v25
	global_store_dwordx4 v[66:67], v[4:7], off offset:32
	v_lshlrev_b32_e32 v24, 16, v25
	v_and_b32_e32 v25, 0xffff0000, v25
	v_lshlrev_b32_e32 v4, 16, v32
	v_and_b32_e32 v5, 0xffff0000, v32
	v_lshlrev_b32_e32 v6, 16, v33
	v_and_b32_e32 v7, 0xffff0000, v33
	v_mul_f32_e32 v4, v84, v4
	v_mul_f32_e32 v5, v85, v5
	v_mul_f32_e32 v6, v86, v6
	v_mul_f32_e32 v7, v87, v7
	v_cvt_pk_bf16_f32 v4, v4, v5
	v_cvt_pk_bf16_f32 v5, v6, v7
	v_lshlrev_b32_e32 v6, 16, v3
	v_and_b32_e32 v7, 0xffff0000, v3
	v_mul_f32_e32 v6, v70, v6
	v_mul_f32_e32 v7, v71, v7
	v_mul_f32_e32 v24, v72, v24
	v_mul_f32_e32 v25, v73, v25
	v_cvt_pk_bf16_f32 v6, v6, v7
	v_cvt_pk_bf16_f32 v7, v24, v25
	v_mov_b32_e32 v3, v22
	v_mov_b32_e32 v22, v23
	v_permlane32_swap_b32_e32 v4, v6
	v_permlane32_swap_b32_e32 v5, v7
	v_permlane32_swap_b32_e32 v20, v3
	v_permlane32_swap_b32_e32 v21, v22
	global_store_dwordx4 v[82:83], v[4:7], off offset:64
	s_nop 1
	v_lshlrev_b32_e32 v4, 16, v20
	v_and_b32_e32 v5, 0xffff0000, v20
	v_lshlrev_b32_e32 v6, 16, v21
	v_and_b32_e32 v7, 0xffff0000, v21
	v_mul_f32_e32 v4, v68, v4
	v_mul_f32_e32 v5, v69, v5
	v_mul_f32_e32 v6, v54, v6
	v_mul_f32_e32 v7, v55, v7
	v_cvt_pk_bf16_f32 v4, v4, v5
	v_cvt_pk_bf16_f32 v5, v6, v7
	v_lshlrev_b32_e32 v6, 16, v3
	v_and_b32_e32 v7, 0xffff0000, v3
	v_lshlrev_b32_e32 v20, 16, v22
	v_and_b32_e32 v21, 0xffff0000, v22
	v_mul_f32_e32 v6, v56, v6
	v_mul_f32_e32 v7, v57, v7
	v_mul_f32_e32 v20, v58, v20
	v_mul_f32_e32 v21, v59, v21
	v_cvt_pk_bf16_f32 v6, v6, v7
	v_cvt_pk_bf16_f32 v7, v20, v21
	v_mov_b32_e32 v3, v14
	v_mov_b32_e32 v14, v15
	v_permlane32_swap_b32_e32 v4, v6
	v_permlane32_swap_b32_e32 v5, v7
	v_permlane32_swap_b32_e32 v12, v3
	v_permlane32_swap_b32_e32 v13, v14
	global_store_dwordx4 v[66:67], v[4:7], off offset:64
	s_nop 1
	v_lshlrev_b32_e32 v4, 16, v12
	v_and_b32_e32 v5, 0xffff0000, v12
	v_lshlrev_b32_e32 v6, 16, v13
	v_and_b32_e32 v7, 0xffff0000, v13
	v_mul_f32_e32 v4, v52, v4
	v_mul_f32_e32 v5, v53, v5
	v_mul_f32_e32 v6, v46, v6
	v_mul_f32_e32 v7, v47, v7
	v_cvt_pk_bf16_f32 v4, v4, v5
	v_cvt_pk_bf16_f32 v5, v6, v7
	v_lshlrev_b32_e32 v6, 16, v3
	v_and_b32_e32 v7, 0xffff0000, v3
	v_lshlrev_b32_e32 v12, 16, v14
	v_and_b32_e32 v13, 0xffff0000, v14
	v_mul_f32_e32 v6, v48, v6
	v_mul_f32_e32 v7, v49, v7
	v_mul_f32_e32 v12, v50, v12
	v_mul_f32_e32 v13, v51, v13
	v_cvt_pk_bf16_f32 v6, v6, v7
	v_cvt_pk_bf16_f32 v7, v12, v13
	v_mov_b32_e32 v3, v10
	v_mov_b32_e32 v10, v11
	v_permlane32_swap_b32_e32 v4, v6
	v_permlane32_swap_b32_e32 v5, v7
	v_permlane32_swap_b32_e32 v8, v3
	v_permlane32_swap_b32_e32 v9, v10
	global_store_dwordx4 v[82:83], v[4:7], off offset:96
	s_nop 1
	v_lshlrev_b32_e32 v4, 16, v8
	v_and_b32_e32 v5, 0xffff0000, v8
	v_lshlrev_b32_e32 v6, 16, v9
	v_and_b32_e32 v7, 0xffff0000, v9
	v_mul_f32_e32 v4, v16, v4
	v_mul_f32_e32 v5, v17, v5
	v_mul_f32_e32 v6, v40, v6
	v_mul_f32_e32 v7, v41, v7
	v_cvt_pk_bf16_f32 v4, v4, v5
	v_cvt_pk_bf16_f32 v5, v6, v7
	v_lshlrev_b32_e32 v6, 16, v3
	v_and_b32_e32 v7, 0xffff0000, v3
	v_lshlrev_b32_e32 v8, 16, v10
	v_and_b32_e32 v9, 0xffff0000, v10
	v_mul_f32_e32 v6, v42, v6
	v_mul_f32_e32 v7, v43, v7
	v_mul_f32_e32 v8, v44, v8
	v_mul_f32_e32 v9, v45, v9
	v_cvt_pk_bf16_f32 v6, v6, v7
	v_cvt_pk_bf16_f32 v7, v8, v9
	s_nop 0
	v_permlane32_swap_b32_e32 v4, v6
	v_permlane32_swap_b32_e32 v5, v7
	global_store_dwordx4 v[66:67], v[4:7], off offset:96
	s_branch .LBB0_621
